# v16: v12 + accumulate-chain MFMA order in the K-loop body of the GEMM copies 1 and 3 (the two k-steps of each accumulator issued back to back, D forwarded into C)
# speedup vs baseline: 1.0053x; 1.0043x over previous
.LBB0_402:
	s_lshl_b32 s54, s41, 7
	s_add_u32 s55, s66, s54
	s_addc_u32 s56, s67, 0
	s_add_u32 s58, s55, 0x100
	ds_read_b128 v[146:149], v142
	ds_read_b128 v[150:153], v142 offset:1024
	ds_read_b128 v[154:157], v142 offset:2048
	ds_read_b128 v[158:161], v142 offset:3072
	ds_read_b128 v[162:165], v143
	ds_read_b128 v[166:169], v143 offset:1024
	ds_read_b128 v[172:175], v143 offset:2048
	ds_read_b128 v[176:179], v143 offset:3072
	s_addc_u32 s59, s56, 0
	s_and_b64 s[52:53], s[84:85], exec
	s_cselect_b32 s91, s43, s59
	s_cselect_b32 s90, s44, s58
	s_add_u32 s52, s12, s54
	s_addc_u32 s53, s13, 0
	s_add_u32 s54, s52, 0x100
	s_addc_u32 s58, s53, 0
	s_and_b64 s[52:53], s[84:85], exec
	s_cselect_b32 s85, s45, s58
	s_cselect_b32 s84, s47, s54
	s_add_u32 s86, s90, 0x80
	s_addc_u32 s87, s91, 0
	s_waitcnt lgkmcnt(0)
	s_add_u32 s88, s84, 0x80
	s_addc_u32 s89, s85, 0
	ds_read_b128 v[180:183], v141
	ds_read_b128 v[184:187], v141 offset:1024
	ds_read_b128 v[188:191], v141 offset:2048
	ds_read_b128 v[196:199], v141 offset:3072
	ds_read_b128 v[200:203], v141 offset:4096
	ds_read_b128 v[204:207], v141 offset:5120
	ds_read_b128 v[208:211], v141 offset:6144
	ds_read_b128 v[212:215], v141 offset:7168
	s_add_u32 s52, s55, 0x40080
	s_addc_u32 s53, s56, 0
	s_add_i32 m0, s16, 0xc000
	s_nop 0
	global_load_lds_dwordx4 v136, s[52:53]
	s_nop 0
	s_add_i32 m0, s16, 0xe000
	s_nop 0
	global_load_lds_dwordx4 v137, s[52:53]
	s_waitcnt vmcnt(8)
	s_waitcnt lgkmcnt(0)
	s_setprio 1
	s_barrier
	v_mfma_f32_16x16x32_bf16 v[128:131], v[146:149], v[180:183], v[128:131]
	v_mfma_f32_16x16x32_bf16 v[128:131], v[150:153], v[184:187], v[128:131]
	v_mfma_f32_16x16x32_bf16 v[120:123], v[154:157], v[180:183], v[120:123]
	v_mfma_f32_16x16x32_bf16 v[120:123], v[158:161], v[184:187], v[120:123]
	v_mfma_f32_16x16x32_bf16 v[112:115], v[146:149], v[188:191], v[112:115]
	v_mfma_f32_16x16x32_bf16 v[112:115], v[150:153], v[196:199], v[112:115]
	v_mfma_f32_16x16x32_bf16 v[104:107], v[154:157], v[188:191], v[104:107]
	v_mfma_f32_16x16x32_bf16 v[104:107], v[158:161], v[196:199], v[104:107]
	v_mfma_f32_16x16x32_bf16 v[96:99], v[146:149], v[200:203], v[96:99]
	v_mfma_f32_16x16x32_bf16 v[96:99], v[150:153], v[204:207], v[96:99]
	v_mfma_f32_16x16x32_bf16 v[88:91], v[154:157], v[200:203], v[88:91]
	v_mfma_f32_16x16x32_bf16 v[88:91], v[158:161], v[204:207], v[88:91]
	v_mfma_f32_16x16x32_bf16 v[64:67], v[146:149], v[208:211], v[64:67]
	v_mfma_f32_16x16x32_bf16 v[64:67], v[150:153], v[212:215], v[64:67]
	v_mfma_f32_16x16x32_bf16 v[56:59], v[154:157], v[208:211], v[56:59]
	v_mfma_f32_16x16x32_bf16 v[56:59], v[158:161], v[212:215], v[56:59]
	v_mfma_f32_16x16x32_bf16 v[124:127], v[162:165], v[180:183], v[124:127]
	v_mfma_f32_16x16x32_bf16 v[124:127], v[166:169], v[184:187], v[124:127]
	v_mfma_f32_16x16x32_bf16 v[116:119], v[172:175], v[180:183], v[116:119]
	v_mfma_f32_16x16x32_bf16 v[116:119], v[176:179], v[184:187], v[116:119]
	v_mfma_f32_16x16x32_bf16 v[108:111], v[162:165], v[188:191], v[108:111]
	v_mfma_f32_16x16x32_bf16 v[108:111], v[166:169], v[196:199], v[108:111]
	v_mfma_f32_16x16x32_bf16 v[100:103], v[172:175], v[188:191], v[100:103]
	v_mfma_f32_16x16x32_bf16 v[100:103], v[176:179], v[196:199], v[100:103]
	v_mfma_f32_16x16x32_bf16 v[92:95], v[162:165], v[200:203], v[92:95]
	v_mfma_f32_16x16x32_bf16 v[92:95], v[166:169], v[204:207], v[92:95]
	v_mfma_f32_16x16x32_bf16 v[84:87], v[172:175], v[200:203], v[84:87]
	v_mfma_f32_16x16x32_bf16 v[84:87], v[176:179], v[204:207], v[84:87]
	v_mfma_f32_16x16x32_bf16 v[60:63], v[162:165], v[208:211], v[60:63]
	v_mfma_f32_16x16x32_bf16 v[60:63], v[166:169], v[212:215], v[60:63]
	v_mfma_f32_16x16x32_bf16 v[52:55], v[172:175], v[208:211], v[52:55]
	v_mfma_f32_16x16x32_bf16 v[52:55], v[176:179], v[212:215], v[52:55]
	s_barrier
	s_setprio 0
	ds_read_b128 v[180:183], v141 offset:16384
	ds_read_b128 v[184:187], v141 offset:17408
	ds_read_b128 v[188:191], v141 offset:18432
	ds_read_b128 v[196:199], v141 offset:19456
	ds_read_b128 v[200:203], v141 offset:20480
	ds_read_b128 v[204:207], v141 offset:21504
	ds_read_b128 v[208:211], v141 offset:22528
	ds_read_b128 v[212:215], v141 offset:23552
	s_add_i32 m0, s16, 0x10000
	s_nop 0
	global_load_lds_dwordx4 v1, s[84:85]
	s_nop 0
	s_add_i32 m0, s16, 0x12000
	s_nop 0
	global_load_lds_dwordx4 v134, s[84:85]
	s_add_u32 s52, s84, 0x40000
	s_addc_u32 s53, s85, 0
	s_add_i32 m0, s16, 0x14000
	s_nop 0
	global_load_lds_dwordx4 v1, s[52:53]
	s_nop 0
	s_add_i32 m0, s16, 0x16000
	s_nop 0
	global_load_lds_dwordx4 v134, s[52:53]
	s_nop 0
	s_add_i32 m0, s16, 0
	s_nop 0
	global_load_lds_dwordx4 v136, s[90:91]
	s_nop 0
	s_add_i32 m0, s16, 0x2000
	s_nop 0
	global_load_lds_dwordx4 v137, s[90:91]
	s_waitcnt vmcnt(8)
	s_waitcnt lgkmcnt(0)
	s_setprio 1
	s_barrier
	v_mfma_f32_16x16x32_bf16 v[80:83], v[146:149], v[180:183], v[80:83]
	v_mfma_f32_16x16x32_bf16 v[80:83], v[150:153], v[184:187], v[80:83]
	v_mfma_f32_16x16x32_bf16 v[72:75], v[154:157], v[180:183], v[72:75]
	v_mfma_f32_16x16x32_bf16 v[72:75], v[158:161], v[184:187], v[72:75]
	v_mfma_f32_16x16x32_bf16 v[48:51], v[146:149], v[188:191], v[48:51]
	v_mfma_f32_16x16x32_bf16 v[48:51], v[150:153], v[196:199], v[48:51]
	v_mfma_f32_16x16x32_bf16 v[40:43], v[154:157], v[188:191], v[40:43]
	v_mfma_f32_16x16x32_bf16 v[40:43], v[158:161], v[196:199], v[40:43]
	v_mfma_f32_16x16x32_bf16 v[32:35], v[146:149], v[200:203], v[32:35]
	v_mfma_f32_16x16x32_bf16 v[32:35], v[150:153], v[204:207], v[32:35]
	v_mfma_f32_16x16x32_bf16 v[24:27], v[154:157], v[200:203], v[24:27]
	v_mfma_f32_16x16x32_bf16 v[24:27], v[158:161], v[204:207], v[24:27]
	v_mfma_f32_16x16x32_bf16 v[16:19], v[146:149], v[208:211], v[16:19]
	v_mfma_f32_16x16x32_bf16 v[16:19], v[150:153], v[212:215], v[16:19]
	v_mfma_f32_16x16x32_bf16 v[8:11], v[154:157], v[208:211], v[8:11]
	v_mfma_f32_16x16x32_bf16 v[8:11], v[158:161], v[212:215], v[8:11]
	v_mfma_f32_16x16x32_bf16 v[76:79], v[162:165], v[180:183], v[76:79]
	v_mfma_f32_16x16x32_bf16 v[76:79], v[166:169], v[184:187], v[76:79]
	v_mfma_f32_16x16x32_bf16 v[68:71], v[172:175], v[180:183], v[68:71]
	v_mfma_f32_16x16x32_bf16 v[68:71], v[176:179], v[184:187], v[68:71]
	v_mfma_f32_16x16x32_bf16 v[44:47], v[162:165], v[188:191], v[44:47]
	v_mfma_f32_16x16x32_bf16 v[44:47], v[166:169], v[196:199], v[44:47]
	v_mfma_f32_16x16x32_bf16 v[36:39], v[172:175], v[188:191], v[36:39]
	v_mfma_f32_16x16x32_bf16 v[36:39], v[176:179], v[196:199], v[36:39]
	v_mfma_f32_16x16x32_bf16 v[28:31], v[162:165], v[200:203], v[28:31]
	v_mfma_f32_16x16x32_bf16 v[28:31], v[166:169], v[204:207], v[28:31]
	v_mfma_f32_16x16x32_bf16 v[20:23], v[172:175], v[200:203], v[20:23]
	v_mfma_f32_16x16x32_bf16 v[20:23], v[176:179], v[204:207], v[20:23]
	v_mfma_f32_16x16x32_bf16 v[12:15], v[162:165], v[208:211], v[12:15]
	v_mfma_f32_16x16x32_bf16 v[12:15], v[166:169], v[212:215], v[12:15]
	v_mfma_f32_16x16x32_bf16 v[4:7], v[172:175], v[208:211], v[4:7]
	v_mfma_f32_16x16x32_bf16 v[4:7], v[176:179], v[212:215], v[4:7]
	s_barrier
	s_setprio 0
	ds_read_b128 v[146:149], v144
	ds_read_b128 v[150:153], v144 offset:1024
	ds_read_b128 v[154:157], v144 offset:2048
	ds_read_b128 v[158:161], v144 offset:3072
	ds_read_b128 v[162:165], v145
	ds_read_b128 v[166:169], v145 offset:1024
	ds_read_b128 v[172:175], v145 offset:2048
	ds_read_b128 v[176:179], v145 offset:3072
	ds_read_b128 v[180:183], v141 offset:32768
	ds_read_b128 v[184:187], v141 offset:33792
	ds_read_b128 v[188:191], v141 offset:34816
	ds_read_b128 v[196:199], v141 offset:35840
	ds_read_b128 v[200:203], v141 offset:36864
	ds_read_b128 v[204:207], v141 offset:37888
	ds_read_b128 v[208:211], v141 offset:38912
	ds_read_b128 v[212:215], v141 offset:39936
	s_add_u32 s52, s90, 0x40000
	s_addc_u32 s53, s91, 0
	s_add_i32 m0, s16, 0x4000
	s_nop 0
	global_load_lds_dwordx4 v136, s[52:53]
	s_nop 0
	s_add_i32 m0, s16, 0x6000
	s_nop 0
	global_load_lds_dwordx4 v137, s[52:53]
	s_waitcnt vmcnt(8)
	s_waitcnt lgkmcnt(0)
	s_setprio 1
	s_barrier
	v_mfma_f32_16x16x32_bf16 v[128:131], v[146:149], v[180:183], v[128:131]
	v_mfma_f32_16x16x32_bf16 v[128:131], v[150:153], v[184:187], v[128:131]
	v_mfma_f32_16x16x32_bf16 v[120:123], v[154:157], v[180:183], v[120:123]
	v_mfma_f32_16x16x32_bf16 v[120:123], v[158:161], v[184:187], v[120:123]
	v_mfma_f32_16x16x32_bf16 v[112:115], v[146:149], v[188:191], v[112:115]
	v_mfma_f32_16x16x32_bf16 v[112:115], v[150:153], v[196:199], v[112:115]
	v_mfma_f32_16x16x32_bf16 v[104:107], v[154:157], v[188:191], v[104:107]
	v_mfma_f32_16x16x32_bf16 v[104:107], v[158:161], v[196:199], v[104:107]
	v_mfma_f32_16x16x32_bf16 v[96:99], v[146:149], v[200:203], v[96:99]
	v_mfma_f32_16x16x32_bf16 v[96:99], v[150:153], v[204:207], v[96:99]
	v_mfma_f32_16x16x32_bf16 v[88:91], v[154:157], v[200:203], v[88:91]
	v_mfma_f32_16x16x32_bf16 v[88:91], v[158:161], v[204:207], v[88:91]
	v_mfma_f32_16x16x32_bf16 v[64:67], v[146:149], v[208:211], v[64:67]
	v_mfma_f32_16x16x32_bf16 v[64:67], v[150:153], v[212:215], v[64:67]
	v_mfma_f32_16x16x32_bf16 v[56:59], v[154:157], v[208:211], v[56:59]
	v_mfma_f32_16x16x32_bf16 v[56:59], v[158:161], v[212:215], v[56:59]
	v_mfma_f32_16x16x32_bf16 v[124:127], v[162:165], v[180:183], v[124:127]
	v_mfma_f32_16x16x32_bf16 v[124:127], v[166:169], v[184:187], v[124:127]
	v_mfma_f32_16x16x32_bf16 v[116:119], v[172:175], v[180:183], v[116:119]
	v_mfma_f32_16x16x32_bf16 v[116:119], v[176:179], v[184:187], v[116:119]
	v_mfma_f32_16x16x32_bf16 v[108:111], v[162:165], v[188:191], v[108:111]
	v_mfma_f32_16x16x32_bf16 v[108:111], v[166:169], v[196:199], v[108:111]
	v_mfma_f32_16x16x32_bf16 v[100:103], v[172:175], v[188:191], v[100:103]
	v_mfma_f32_16x16x32_bf16 v[100:103], v[176:179], v[196:199], v[100:103]
	v_mfma_f32_16x16x32_bf16 v[92:95], v[162:165], v[200:203], v[92:95]
	v_mfma_f32_16x16x32_bf16 v[92:95], v[166:169], v[204:207], v[92:95]
	v_mfma_f32_16x16x32_bf16 v[84:87], v[172:175], v[200:203], v[84:87]
	v_mfma_f32_16x16x32_bf16 v[84:87], v[176:179], v[204:207], v[84:87]
	v_mfma_f32_16x16x32_bf16 v[60:63], v[162:165], v[208:211], v[60:63]
	v_mfma_f32_16x16x32_bf16 v[60:63], v[166:169], v[212:215], v[60:63]
	v_mfma_f32_16x16x32_bf16 v[52:55], v[172:175], v[208:211], v[52:55]
	v_mfma_f32_16x16x32_bf16 v[52:55], v[176:179], v[212:215], v[52:55]
	s_barrier
	s_setprio 0
	ds_read_b128 v[180:183], v141 offset:49152
	ds_read_b128 v[184:187], v141 offset:50176
	ds_read_b128 v[188:191], v141 offset:51200
	ds_read_b128 v[196:199], v141 offset:52224
	ds_read_b128 v[200:203], v141 offset:53248
	ds_read_b128 v[204:207], v141 offset:54272
	ds_read_b128 v[208:211], v141 offset:55296
	ds_read_b128 v[212:215], v141 offset:56320
	s_add_i32 m0, s16, 0x18000
	s_nop 0
	global_load_lds_dwordx4 v1, s[88:89]
	s_nop 0
	s_add_i32 m0, s16, 0x1a000
	s_nop 0
	global_load_lds_dwordx4 v134, s[88:89]
	s_add_u32 s52, s84, 0x40080
	s_addc_u32 s53, s85, 0
	s_add_i32 m0, s16, 0x1c000
	s_nop 0
	global_load_lds_dwordx4 v1, s[52:53]
	s_nop 0
	s_add_i32 m0, s16, 0x1e000
	s_nop 0
	global_load_lds_dwordx4 v134, s[52:53]
	s_nop 0
	s_add_i32 m0, s16, 0x8000
	s_nop 0
	global_load_lds_dwordx4 v136, s[86:87]
	s_nop 0
	s_add_i32 m0, s16, 0xa000
	s_nop 0
	global_load_lds_dwordx4 v137, s[86:87]
	s_waitcnt vmcnt(8)
	s_waitcnt lgkmcnt(0)
	s_setprio 1
	s_barrier
	v_mfma_f32_16x16x32_bf16 v[80:83], v[146:149], v[180:183], v[80:83]
	v_mfma_f32_16x16x32_bf16 v[80:83], v[150:153], v[184:187], v[80:83]
	v_mfma_f32_16x16x32_bf16 v[72:75], v[154:157], v[180:183], v[72:75]
	v_mfma_f32_16x16x32_bf16 v[72:75], v[158:161], v[184:187], v[72:75]
	v_mfma_f32_16x16x32_bf16 v[48:51], v[146:149], v[188:191], v[48:51]
	v_mfma_f32_16x16x32_bf16 v[48:51], v[150:153], v[196:199], v[48:51]
	v_mfma_f32_16x16x32_bf16 v[40:43], v[154:157], v[188:191], v[40:43]
	v_mfma_f32_16x16x32_bf16 v[40:43], v[158:161], v[196:199], v[40:43]
	v_mfma_f32_16x16x32_bf16 v[32:35], v[146:149], v[200:203], v[32:35]
	v_mfma_f32_16x16x32_bf16 v[32:35], v[150:153], v[204:207], v[32:35]
	v_mfma_f32_16x16x32_bf16 v[24:27], v[154:157], v[200:203], v[24:27]
	v_mfma_f32_16x16x32_bf16 v[24:27], v[158:161], v[204:207], v[24:27]
	v_mfma_f32_16x16x32_bf16 v[16:19], v[146:149], v[208:211], v[16:19]
	v_mfma_f32_16x16x32_bf16 v[16:19], v[150:153], v[212:215], v[16:19]
	v_mfma_f32_16x16x32_bf16 v[8:11], v[154:157], v[208:211], v[8:11]
	v_mfma_f32_16x16x32_bf16 v[8:11], v[158:161], v[212:215], v[8:11]
	v_mfma_f32_16x16x32_bf16 v[76:79], v[162:165], v[180:183], v[76:79]
	v_mfma_f32_16x16x32_bf16 v[76:79], v[166:169], v[184:187], v[76:79]
	v_mfma_f32_16x16x32_bf16 v[68:71], v[172:175], v[180:183], v[68:71]
	v_mfma_f32_16x16x32_bf16 v[68:71], v[176:179], v[184:187], v[68:71]
	v_mfma_f32_16x16x32_bf16 v[44:47], v[162:165], v[188:191], v[44:47]
	v_mfma_f32_16x16x32_bf16 v[44:47], v[166:169], v[196:199], v[44:47]
	v_mfma_f32_16x16x32_bf16 v[36:39], v[172:175], v[188:191], v[36:39]
	v_mfma_f32_16x16x32_bf16 v[36:39], v[176:179], v[196:199], v[36:39]
	v_mfma_f32_16x16x32_bf16 v[28:31], v[162:165], v[200:203], v[28:31]
	v_mfma_f32_16x16x32_bf16 v[28:31], v[166:169], v[204:207], v[28:31]
	v_mfma_f32_16x16x32_bf16 v[20:23], v[172:175], v[200:203], v[20:23]
	v_mfma_f32_16x16x32_bf16 v[20:23], v[176:179], v[204:207], v[20:23]
	v_mfma_f32_16x16x32_bf16 v[12:15], v[162:165], v[208:211], v[12:15]
	v_mfma_f32_16x16x32_bf16 v[12:15], v[166:169], v[212:215], v[12:15]
	v_mfma_f32_16x16x32_bf16 v[4:7], v[172:175], v[208:211], v[4:7]
	v_mfma_f32_16x16x32_bf16 v[4:7], v[176:179], v[212:215], v[4:7]
	s_barrier
	s_setprio 0
	s_add_i32 s52, s41, 2
	s_cmp_gt_u32 s41, 13
	s_cbranch_scc1 .LBB0_404
	s_mov_b32 s41, s52
	s_branch .LBB0_383

.LBB0_730:
	s_or_b32 s20, s90, 1
	s_add_i32 s90, s90, 2
	s_mov_b32 s91, s21
	ds_read_b128 v[142:145], v137
	ds_read_b128 v[146:149], v137 offset:1024
	ds_read_b128 v[150:153], v137 offset:2048
	ds_read_b128 v[154:157], v137 offset:3072
	ds_read_b128 v[158:161], v138
	ds_read_b128 v[162:165], v138 offset:1024
	ds_read_b128 v[166:169], v138 offset:2048
	ds_read_b128 v[172:175], v138 offset:3072
	s_lshl_b64 s[96:97], s[20:21], 7
	s_lshl_b64 s[2:3], s[90:91], 7
	s_add_u32 s20, s78, s2
	s_addc_u32 s73, s79, s3
	s_and_b64 s[12:13], s[92:93], exec
	s_cselect_b32 s95, s73, s87
	s_cselect_b32 s94, s20, s86
	s_add_u32 s12, s76, s2
	s_addc_u32 s13, s77, s3
	s_and_b64 s[2:3], s[92:93], exec
	s_cselect_b32 s93, s13, s89
	s_cselect_b32 s92, s12, s88
	s_add_u32 s2, s94, 0x80
	s_addc_u32 s3, s95, 0
	s_add_u32 s12, s92, 0x80
	s_addc_u32 s13, s93, 0
	ds_read_b128 v[176:179], v136
	ds_read_b128 v[180:183], v136 offset:1024
	ds_read_b128 v[184:187], v136 offset:2048
	ds_read_b128 v[188:191], v136 offset:3072
	ds_read_b128 v[196:199], v136 offset:4096
	ds_read_b128 v[200:203], v136 offset:5120
	ds_read_b128 v[204:207], v136 offset:6144
	ds_read_b128 v[208:211], v136 offset:7168
	s_add_u32 s96, s59, s96
	s_addc_u32 s97, s38, s97
	s_add_i32 m0, s43, 0xc000
	s_nop 0
	global_load_lds_dwordx4 v134, s[96:97]
	s_nop 0
	s_add_i32 m0, s43, 0xe000
	s_nop 0
	global_load_lds_dwordx4 v135, s[96:97]
	s_waitcnt vmcnt(8)
	s_waitcnt lgkmcnt(0)
	s_setprio 1
	s_barrier
	v_mfma_f32_16x16x32_bf16 v[70:73], v[142:145], v[176:179], v[70:73]
	v_mfma_f32_16x16x32_bf16 v[70:73], v[146:149], v[180:183], v[70:73]
	v_mfma_f32_16x16x32_bf16 v[86:89], v[150:153], v[176:179], v[86:89]
	v_mfma_f32_16x16x32_bf16 v[86:89], v[154:157], v[180:183], v[86:89]
	v_mfma_f32_16x16x32_bf16 v[74:77], v[142:145], v[184:187], v[74:77]
	v_mfma_f32_16x16x32_bf16 v[74:77], v[146:149], v[188:191], v[74:77]
	v_mfma_f32_16x16x32_bf16 v[90:93], v[150:153], v[184:187], v[90:93]
	v_mfma_f32_16x16x32_bf16 v[90:93], v[154:157], v[188:191], v[90:93]
	v_mfma_f32_16x16x32_bf16 v[78:81], v[142:145], v[196:199], v[78:81]
	v_mfma_f32_16x16x32_bf16 v[78:81], v[146:149], v[200:203], v[78:81]
	v_mfma_f32_16x16x32_bf16 v[94:97], v[150:153], v[196:199], v[94:97]
	v_mfma_f32_16x16x32_bf16 v[94:97], v[154:157], v[200:203], v[94:97]
	v_mfma_f32_16x16x32_bf16 v[82:85], v[142:145], v[204:207], v[82:85]
	v_mfma_f32_16x16x32_bf16 v[82:85], v[146:149], v[208:211], v[82:85]
	v_mfma_f32_16x16x32_bf16 v[98:101], v[150:153], v[204:207], v[98:101]
	v_mfma_f32_16x16x32_bf16 v[98:101], v[154:157], v[208:211], v[98:101]
	v_mfma_f32_16x16x32_bf16 v[102:105], v[158:161], v[176:179], v[102:105]
	v_mfma_f32_16x16x32_bf16 v[102:105], v[162:165], v[180:183], v[102:105]
	v_mfma_f32_16x16x32_bf16 v[118:121], v[166:169], v[176:179], v[118:121]
	v_mfma_f32_16x16x32_bf16 v[118:121], v[172:175], v[180:183], v[118:121]
	v_mfma_f32_16x16x32_bf16 v[106:109], v[158:161], v[184:187], v[106:109]
	v_mfma_f32_16x16x32_bf16 v[106:109], v[162:165], v[188:191], v[106:109]
	v_mfma_f32_16x16x32_bf16 v[122:125], v[166:169], v[184:187], v[122:125]
	v_mfma_f32_16x16x32_bf16 v[122:125], v[172:175], v[188:191], v[122:125]
	v_mfma_f32_16x16x32_bf16 v[110:113], v[158:161], v[196:199], v[110:113]
	v_mfma_f32_16x16x32_bf16 v[110:113], v[162:165], v[200:203], v[110:113]
	v_mfma_f32_16x16x32_bf16 v[126:129], v[166:169], v[196:199], v[126:129]
	v_mfma_f32_16x16x32_bf16 v[126:129], v[172:175], v[200:203], v[126:129]
	v_mfma_f32_16x16x32_bf16 v[114:117], v[158:161], v[204:207], v[114:117]
	v_mfma_f32_16x16x32_bf16 v[114:117], v[162:165], v[208:211], v[114:117]
	v_mfma_f32_16x16x32_bf16 v[130:133], v[166:169], v[204:207], v[130:133]
	v_mfma_f32_16x16x32_bf16 v[130:133], v[172:175], v[208:211], v[130:133]
	s_barrier
	s_setprio 0
	ds_read_b128 v[176:179], v136 offset:16384
	ds_read_b128 v[180:183], v136 offset:17408
	ds_read_b128 v[184:187], v136 offset:18432
	ds_read_b128 v[188:191], v136 offset:19456
	ds_read_b128 v[196:199], v136 offset:20480
	ds_read_b128 v[200:203], v136 offset:21504
	ds_read_b128 v[204:207], v136 offset:22528
	ds_read_b128 v[208:211], v136 offset:23552
	s_add_i32 m0, s43, 0x10000
	s_nop 0
	global_load_lds_dwordx4 v134, s[92:93]
	s_nop 0
	s_add_i32 m0, s43, 0x12000
	s_nop 0
	global_load_lds_dwordx4 v135, s[92:93]
	s_add_u32 s92, s92, s16
	s_addc_u32 s93, s93, 0
	s_add_i32 m0, s43, 0x14000
	s_nop 0
	global_load_lds_dwordx4 v134, s[92:93]
	s_nop 0
	s_add_i32 m0, s43, 0x16000
	s_nop 0
	global_load_lds_dwordx4 v135, s[92:93]
	s_nop 0
	s_add_i32 m0, s43, 0
	s_nop 0
	global_load_lds_dwordx4 v134, s[94:95]
	s_nop 0
	s_add_i32 m0, s43, 0x2000
	s_nop 0
	global_load_lds_dwordx4 v135, s[94:95]
	s_waitcnt vmcnt(8)
	s_waitcnt lgkmcnt(0)
	s_setprio 1
	s_barrier
	v_mfma_f32_16x16x32_bf16 v[4:7], v[142:145], v[176:179], v[6:9]
	v_mfma_f32_16x16x32_bf16 v[22:25], v[150:153], v[176:179], v[22:25]
	v_mfma_f32_16x16x32_bf16 v[8:11], v[142:145], v[184:187], v[10:13]
	v_mfma_f32_16x16x32_bf16 v[26:29], v[150:153], v[184:187], v[26:29]
	v_mfma_f32_16x16x32_bf16 v[14:17], v[142:145], v[196:199], v[14:17]
	v_mfma_f32_16x16x32_bf16 v[30:33], v[150:153], v[196:199], v[30:33]
	v_mfma_f32_16x16x32_bf16 v[18:21], v[142:145], v[204:207], v[18:21]
	v_mfma_f32_16x16x32_bf16 v[34:37], v[150:153], v[204:207], v[34:37]
	v_mfma_f32_16x16x32_bf16 v[4:7], v[146:149], v[180:183], v[4:7]
	v_mfma_f32_16x16x32_bf16 v[22:25], v[154:157], v[180:183], v[22:25]
	v_mfma_f32_16x16x32_bf16 v[10:13], v[146:149], v[188:191], v[8:11]
	v_mfma_f32_16x16x32_bf16 v[26:29], v[154:157], v[188:191], v[26:29]
	v_mfma_f32_16x16x32_bf16 v[14:17], v[146:149], v[200:203], v[14:17]
	v_mfma_f32_16x16x32_bf16 v[30:33], v[154:157], v[200:203], v[30:33]
	v_mfma_f32_16x16x32_bf16 v[18:21], v[146:149], v[208:211], v[18:21]
	v_mfma_f32_16x16x32_bf16 v[34:37], v[154:157], v[208:211], v[34:37]
	v_mfma_f32_16x16x32_bf16 v[38:41], v[158:161], v[176:179], v[38:41]
	v_mfma_f32_16x16x32_bf16 v[54:57], v[166:169], v[176:179], v[54:57]
	v_mfma_f32_16x16x32_bf16 v[42:45], v[158:161], v[184:187], v[42:45]
	v_mfma_f32_16x16x32_bf16 v[58:61], v[166:169], v[184:187], v[58:61]
	v_mfma_f32_16x16x32_bf16 v[46:49], v[158:161], v[196:199], v[46:49]
	v_mfma_f32_16x16x32_bf16 v[62:65], v[166:169], v[196:199], v[62:65]
	v_mfma_f32_16x16x32_bf16 v[50:53], v[158:161], v[204:207], v[50:53]
	v_mfma_f32_16x16x32_bf16 v[66:69], v[166:169], v[204:207], v[66:69]
	v_mfma_f32_16x16x32_bf16 v[38:41], v[162:165], v[180:183], v[38:41]
	v_mfma_f32_16x16x32_bf16 v[54:57], v[172:175], v[180:183], v[54:57]
	v_mfma_f32_16x16x32_bf16 v[42:45], v[162:165], v[188:191], v[42:45]
	v_mfma_f32_16x16x32_bf16 v[58:61], v[172:175], v[188:191], v[58:61]
	v_mfma_f32_16x16x32_bf16 v[46:49], v[162:165], v[200:203], v[46:49]
	v_mfma_f32_16x16x32_bf16 v[62:65], v[172:175], v[200:203], v[62:65]
	v_mfma_f32_16x16x32_bf16 v[50:53], v[162:165], v[208:211], v[50:53]
	v_mfma_f32_16x16x32_bf16 v[66:69], v[172:175], v[208:211], v[66:69]
	s_barrier
	s_setprio 0
	ds_read_b128 v[142:145], v139
	ds_read_b128 v[146:149], v139 offset:1024
	ds_read_b128 v[150:153], v139 offset:2048
	ds_read_b128 v[154:157], v139 offset:3072
	ds_read_b128 v[158:161], v140
	ds_read_b128 v[162:165], v140 offset:1024
	ds_read_b128 v[166:169], v140 offset:2048
	ds_read_b128 v[172:175], v140 offset:3072
	ds_read_b128 v[176:179], v136 offset:32768
	ds_read_b128 v[180:183], v136 offset:33792
	ds_read_b128 v[184:187], v136 offset:34816
	ds_read_b128 v[188:191], v136 offset:35840
	ds_read_b128 v[196:199], v136 offset:36864
	ds_read_b128 v[200:203], v136 offset:37888
	ds_read_b128 v[204:207], v136 offset:38912
	ds_read_b128 v[208:211], v136 offset:39936
	s_add_u32 s92, s94, s16
	s_addc_u32 s93, s95, 0
	s_add_i32 m0, s43, 0x4000
	s_nop 0
	global_load_lds_dwordx4 v134, s[92:93]
	s_nop 0
	s_add_i32 m0, s43, 0x6000
	s_nop 0
	global_load_lds_dwordx4 v135, s[92:93]
	s_waitcnt vmcnt(8)
	s_waitcnt lgkmcnt(0)
	s_setprio 1
	s_barrier
	v_mfma_f32_16x16x32_bf16 v[70:73], v[142:145], v[176:179], v[70:73]
	v_mfma_f32_16x16x32_bf16 v[70:73], v[146:149], v[180:183], v[70:73]
	v_mfma_f32_16x16x32_bf16 v[86:89], v[150:153], v[176:179], v[86:89]
	v_mfma_f32_16x16x32_bf16 v[86:89], v[154:157], v[180:183], v[86:89]
	v_mfma_f32_16x16x32_bf16 v[74:77], v[142:145], v[184:187], v[74:77]
	v_mfma_f32_16x16x32_bf16 v[74:77], v[146:149], v[188:191], v[74:77]
	v_mfma_f32_16x16x32_bf16 v[90:93], v[150:153], v[184:187], v[90:93]
	v_mfma_f32_16x16x32_bf16 v[90:93], v[154:157], v[188:191], v[90:93]
	v_mfma_f32_16x16x32_bf16 v[78:81], v[142:145], v[196:199], v[78:81]
	v_mfma_f32_16x16x32_bf16 v[78:81], v[146:149], v[200:203], v[78:81]
	v_mfma_f32_16x16x32_bf16 v[94:97], v[150:153], v[196:199], v[94:97]
	v_mfma_f32_16x16x32_bf16 v[94:97], v[154:157], v[200:203], v[94:97]
	v_mfma_f32_16x16x32_bf16 v[82:85], v[142:145], v[204:207], v[82:85]
	v_mfma_f32_16x16x32_bf16 v[82:85], v[146:149], v[208:211], v[82:85]
	v_mfma_f32_16x16x32_bf16 v[98:101], v[150:153], v[204:207], v[98:101]
	v_mfma_f32_16x16x32_bf16 v[98:101], v[154:157], v[208:211], v[98:101]
	v_mfma_f32_16x16x32_bf16 v[102:105], v[158:161], v[176:179], v[102:105]
	v_mfma_f32_16x16x32_bf16 v[102:105], v[162:165], v[180:183], v[102:105]
	v_mfma_f32_16x16x32_bf16 v[118:121], v[166:169], v[176:179], v[118:121]
	v_mfma_f32_16x16x32_bf16 v[118:121], v[172:175], v[180:183], v[118:121]
	v_mfma_f32_16x16x32_bf16 v[106:109], v[158:161], v[184:187], v[106:109]
	v_mfma_f32_16x16x32_bf16 v[106:109], v[162:165], v[188:191], v[106:109]
	v_mfma_f32_16x16x32_bf16 v[122:125], v[166:169], v[184:187], v[122:125]
	v_mfma_f32_16x16x32_bf16 v[122:125], v[172:175], v[188:191], v[122:125]
	v_mfma_f32_16x16x32_bf16 v[110:113], v[158:161], v[196:199], v[110:113]
	v_mfma_f32_16x16x32_bf16 v[110:113], v[162:165], v[200:203], v[110:113]
	v_mfma_f32_16x16x32_bf16 v[126:129], v[166:169], v[196:199], v[126:129]
	v_mfma_f32_16x16x32_bf16 v[126:129], v[172:175], v[200:203], v[126:129]
	v_mfma_f32_16x16x32_bf16 v[114:117], v[158:161], v[204:207], v[114:117]
	v_mfma_f32_16x16x32_bf16 v[114:117], v[162:165], v[208:211], v[114:117]
	v_mfma_f32_16x16x32_bf16 v[130:133], v[166:169], v[204:207], v[130:133]
	v_mfma_f32_16x16x32_bf16 v[130:133], v[172:175], v[208:211], v[130:133]
	s_barrier
	s_setprio 0
	ds_read_b128 v[176:179], v136 offset:49152
	ds_read_b128 v[180:183], v136 offset:50176
	ds_read_b128 v[184:187], v136 offset:51200
	ds_read_b128 v[188:191], v136 offset:52224
	ds_read_b128 v[196:199], v136 offset:53248
	ds_read_b128 v[200:203], v136 offset:54272
	ds_read_b128 v[204:207], v136 offset:55296
	ds_read_b128 v[208:211], v136 offset:56320
	s_add_i32 m0, s43, 0x18000
	s_nop 0
	global_load_lds_dwordx4 v134, s[12:13]
	s_nop 0
	s_add_i32 m0, s43, 0x1a000
	s_nop 0
	global_load_lds_dwordx4 v135, s[12:13]
	s_add_u32 s12, s12, s16
	s_addc_u32 s13, s13, 0
	s_add_i32 m0, s43, 0x1c000
	s_nop 0
	global_load_lds_dwordx4 v134, s[12:13]
	s_nop 0
	s_add_i32 m0, s43, 0x1e000
	s_nop 0
	global_load_lds_dwordx4 v135, s[12:13]
	s_nop 0
	s_add_i32 m0, s43, 0x8000
	s_nop 0
	global_load_lds_dwordx4 v134, s[2:3]
	s_nop 0
	s_add_i32 m0, s43, 0xa000
	s_nop 0
	global_load_lds_dwordx4 v135, s[2:3]
	s_waitcnt vmcnt(8)
	s_waitcnt lgkmcnt(0)
	s_setprio 1
	s_barrier
	v_mfma_f32_16x16x32_bf16 v[4:7], v[142:145], v[176:179], v[4:7]
	v_mfma_f32_16x16x32_bf16 v[22:25], v[150:153], v[176:179], v[22:25]
	v_mfma_f32_16x16x32_bf16 v[10:13], v[142:145], v[184:187], v[10:13]
	v_mfma_f32_16x16x32_bf16 v[26:29], v[150:153], v[184:187], v[26:29]
	v_mfma_f32_16x16x32_bf16 v[14:17], v[142:145], v[196:199], v[14:17]
	v_mfma_f32_16x16x32_bf16 v[30:33], v[150:153], v[196:199], v[30:33]
	v_mfma_f32_16x16x32_bf16 v[18:21], v[142:145], v[204:207], v[18:21]
	v_mfma_f32_16x16x32_bf16 v[34:37], v[150:153], v[204:207], v[34:37]
	v_mfma_f32_16x16x32_bf16 v[6:9], v[146:149], v[180:183], v[4:7]
	v_mfma_f32_16x16x32_bf16 v[22:25], v[154:157], v[180:183], v[22:25]
	v_mfma_f32_16x16x32_bf16 v[10:13], v[146:149], v[188:191], v[10:13]
	v_mfma_f32_16x16x32_bf16 v[26:29], v[154:157], v[188:191], v[26:29]
	v_mfma_f32_16x16x32_bf16 v[14:17], v[146:149], v[200:203], v[14:17]
	v_mfma_f32_16x16x32_bf16 v[30:33], v[154:157], v[200:203], v[30:33]
	v_mfma_f32_16x16x32_bf16 v[18:21], v[146:149], v[208:211], v[18:21]
	v_mfma_f32_16x16x32_bf16 v[34:37], v[154:157], v[208:211], v[34:37]
	v_mfma_f32_16x16x32_bf16 v[38:41], v[158:161], v[176:179], v[38:41]
	v_mfma_f32_16x16x32_bf16 v[54:57], v[166:169], v[176:179], v[54:57]
	v_mfma_f32_16x16x32_bf16 v[42:45], v[158:161], v[184:187], v[42:45]
	v_mfma_f32_16x16x32_bf16 v[58:61], v[166:169], v[184:187], v[58:61]
	v_mfma_f32_16x16x32_bf16 v[46:49], v[158:161], v[196:199], v[46:49]
	v_mfma_f32_16x16x32_bf16 v[62:65], v[166:169], v[196:199], v[62:65]
	v_mfma_f32_16x16x32_bf16 v[50:53], v[158:161], v[204:207], v[50:53]
	v_mfma_f32_16x16x32_bf16 v[66:69], v[166:169], v[204:207], v[66:69]
	v_mfma_f32_16x16x32_bf16 v[38:41], v[162:165], v[180:183], v[38:41]
	v_mfma_f32_16x16x32_bf16 v[54:57], v[172:175], v[180:183], v[54:57]
	v_mfma_f32_16x16x32_bf16 v[42:45], v[162:165], v[188:191], v[42:45]
	v_mfma_f32_16x16x32_bf16 v[58:61], v[172:175], v[188:191], v[58:61]
	v_mfma_f32_16x16x32_bf16 v[46:49], v[162:165], v[200:203], v[46:49]
	v_mfma_f32_16x16x32_bf16 v[62:65], v[172:175], v[200:203], v[62:65]
	v_mfma_f32_16x16x32_bf16 v[50:53], v[162:165], v[208:211], v[50:53]
	v_mfma_f32_16x16x32_bf16 v[66:69], v[172:175], v[208:211], v[66:69]
	s_barrier
	s_setprio 0
	s_cmp_ge_u32 s90, s55
	s_cbranch_scc1 .LBB0_848

.LBB0_1192:
	s_lshl_b32 s12, s29, 7
	s_add_u32 s90, s62, s12
	s_addc_u32 s91, s63, 0
	s_add_u32 s13, s90, 0x100
	ds_read_b128 v[138:141], v134
	ds_read_b128 v[142:145], v134 offset:1024
	ds_read_b128 v[154:157], v134 offset:2048
	ds_read_b128 v[158:161], v134 offset:3072
	ds_read_b128 v[162:165], v135
	ds_read_b128 v[166:169], v135 offset:1024
	ds_read_b128 v[172:175], v135 offset:2048
	ds_read_b128 v[176:179], v135 offset:3072
	s_addc_u32 s88, s91, 0
	s_and_b64 s[2:3], s[86:87], exec
	s_cselect_b32 s89, s33, s88
	s_cselect_b32 s88, s39, s13
	s_add_u32 s2, s64, s12
	s_addc_u32 s3, s65, 0
	s_add_u32 s12, s2, 0x100
	s_addc_u32 s13, s3, 0
	s_and_b64 s[2:3], s[86:87], exec
	s_cselect_b32 s3, s54, s13
	s_cselect_b32 s2, s47, s12
	s_add_u32 s12, s88, 0x80
	s_addc_u32 s13, s89, 0
	s_add_u32 s86, s2, 0x80
	s_addc_u32 s87, s3, 0
	ds_read_b128 v[180:183], v152
	ds_read_b128 v[184:187], v152 offset:1024
	ds_read_b128 v[196:199], v152 offset:2048
	ds_read_b128 v[200:203], v152 offset:3072
	ds_read_b128 v[204:207], v152 offset:4096
	ds_read_b128 v[208:211], v152 offset:5120
	ds_read_b128 v[212:215], v152 offset:6144
	ds_read_b128 v[216:219], v152 offset:7168
	s_add_u32 s90, s90, 0x40080
	s_addc_u32 s91, s91, 0
	s_add_i32 m0, s69, 0xc000
	s_nop 0
	global_load_lds_dwordx4 v147, s[90:91]
	s_nop 0
	s_add_i32 m0, s69, 0xe000
	s_nop 0
	global_load_lds_dwordx4 v148, s[90:91]
	s_waitcnt vmcnt(8)
	s_waitcnt lgkmcnt(0)
	s_setprio 1
	s_barrier
	v_mfma_f32_16x16x32_bf16 v[124:127], v[138:141], v[180:183], v[124:127]
	v_mfma_f32_16x16x32_bf16 v[124:127], v[142:145], v[184:187], v[124:127]
	v_mfma_f32_16x16x32_bf16 v[116:119], v[154:157], v[180:183], v[116:119]
	v_mfma_f32_16x16x32_bf16 v[116:119], v[158:161], v[184:187], v[116:119]
	v_mfma_f32_16x16x32_bf16 v[108:111], v[138:141], v[196:199], v[108:111]
	v_mfma_f32_16x16x32_bf16 v[108:111], v[142:145], v[200:203], v[108:111]
	v_mfma_f32_16x16x32_bf16 v[100:103], v[154:157], v[196:199], v[100:103]
	v_mfma_f32_16x16x32_bf16 v[100:103], v[158:161], v[200:203], v[100:103]
	v_mfma_f32_16x16x32_bf16 v[92:95], v[138:141], v[204:207], v[92:95]
	v_mfma_f32_16x16x32_bf16 v[92:95], v[142:145], v[208:211], v[92:95]
	v_mfma_f32_16x16x32_bf16 v[84:87], v[154:157], v[204:207], v[84:87]
	v_mfma_f32_16x16x32_bf16 v[84:87], v[158:161], v[208:211], v[84:87]
	v_mfma_f32_16x16x32_bf16 v[76:79], v[138:141], v[212:215], v[76:79]
	v_mfma_f32_16x16x32_bf16 v[76:79], v[142:145], v[216:219], v[76:79]
	v_mfma_f32_16x16x32_bf16 v[64:67], v[154:157], v[212:215], v[64:67]
	v_mfma_f32_16x16x32_bf16 v[64:67], v[158:161], v[216:219], v[64:67]
	v_mfma_f32_16x16x32_bf16 v[128:131], v[162:165], v[180:183], v[128:131]
	v_mfma_f32_16x16x32_bf16 v[128:131], v[166:169], v[184:187], v[128:131]
	v_mfma_f32_16x16x32_bf16 v[120:123], v[172:175], v[180:183], v[120:123]
	v_mfma_f32_16x16x32_bf16 v[120:123], v[176:179], v[184:187], v[120:123]
	v_mfma_f32_16x16x32_bf16 v[112:115], v[162:165], v[196:199], v[112:115]
	v_mfma_f32_16x16x32_bf16 v[112:115], v[166:169], v[200:203], v[112:115]
	v_mfma_f32_16x16x32_bf16 v[104:107], v[172:175], v[196:199], v[104:107]
	v_mfma_f32_16x16x32_bf16 v[104:107], v[176:179], v[200:203], v[104:107]
	v_mfma_f32_16x16x32_bf16 v[96:99], v[162:165], v[204:207], v[96:99]
	v_mfma_f32_16x16x32_bf16 v[96:99], v[166:169], v[208:211], v[96:99]
	v_mfma_f32_16x16x32_bf16 v[88:91], v[172:175], v[204:207], v[88:91]
	v_mfma_f32_16x16x32_bf16 v[88:91], v[176:179], v[208:211], v[88:91]
	v_mfma_f32_16x16x32_bf16 v[80:83], v[162:165], v[212:215], v[80:83]
	v_mfma_f32_16x16x32_bf16 v[80:83], v[166:169], v[216:219], v[80:83]
	v_mfma_f32_16x16x32_bf16 v[72:75], v[172:175], v[212:215], v[72:75]
	v_mfma_f32_16x16x32_bf16 v[72:75], v[176:179], v[216:219], v[72:75]
	s_barrier
	s_setprio 0
	ds_read_b128 v[180:183], v152 offset:16384
	ds_read_b128 v[184:187], v152 offset:17408
	ds_read_b128 v[196:199], v152 offset:18432
	ds_read_b128 v[200:203], v152 offset:19456
	ds_read_b128 v[204:207], v152 offset:20480
	ds_read_b128 v[208:211], v152 offset:21504
	ds_read_b128 v[212:215], v152 offset:22528
	ds_read_b128 v[216:219], v152 offset:23552
	s_add_i32 m0, s69, 0x10000
	s_nop 0
	global_load_lds_dwordx4 v1, s[2:3]
	s_nop 0
	s_add_i32 m0, s69, 0x12000
	s_nop 0
	global_load_lds_dwordx4 v146, s[2:3]
	s_add_u32 s90, s2, 0x40000
	s_addc_u32 s91, s3, 0
	s_add_i32 m0, s69, 0x14000
	s_nop 0
	global_load_lds_dwordx4 v1, s[90:91]
	s_nop 0
	s_add_i32 m0, s69, 0x16000
	s_nop 0
	global_load_lds_dwordx4 v146, s[90:91]
	s_nop 0
	s_add_i32 m0, s69, 0
	s_nop 0
	global_load_lds_dwordx4 v147, s[88:89]
	s_nop 0
	s_add_i32 m0, s69, 0x2000
	s_nop 0
	global_load_lds_dwordx4 v148, s[88:89]
	s_waitcnt vmcnt(8)
	s_waitcnt lgkmcnt(0)
	s_setprio 1
	s_barrier
	v_mfma_f32_16x16x32_bf16 v[60:63], v[138:141], v[180:183], v[60:63]
	v_mfma_f32_16x16x32_bf16 v[60:63], v[142:145], v[184:187], v[60:63]
	v_mfma_f32_16x16x32_bf16 v[52:55], v[154:157], v[180:183], v[52:55]
	v_mfma_f32_16x16x32_bf16 v[52:55], v[158:161], v[184:187], v[52:55]
	v_mfma_f32_16x16x32_bf16 v[44:47], v[138:141], v[196:199], v[44:47]
	v_mfma_f32_16x16x32_bf16 v[44:47], v[142:145], v[200:203], v[44:47]
	v_mfma_f32_16x16x32_bf16 v[36:39], v[154:157], v[196:199], v[36:39]
	v_mfma_f32_16x16x32_bf16 v[36:39], v[158:161], v[200:203], v[36:39]
	v_mfma_f32_16x16x32_bf16 v[28:31], v[138:141], v[204:207], v[28:31]
	v_mfma_f32_16x16x32_bf16 v[28:31], v[142:145], v[208:211], v[28:31]
	v_mfma_f32_16x16x32_bf16 v[20:23], v[154:157], v[204:207], v[20:23]
	v_mfma_f32_16x16x32_bf16 v[20:23], v[158:161], v[208:211], v[20:23]
	v_mfma_f32_16x16x32_bf16 v[12:15], v[138:141], v[212:215], v[12:15]
	v_mfma_f32_16x16x32_bf16 v[12:15], v[142:145], v[216:219], v[12:15]
	v_mfma_f32_16x16x32_bf16 v[4:7], v[154:157], v[212:215], v[4:7]
	v_mfma_f32_16x16x32_bf16 v[4:7], v[158:161], v[216:219], v[4:7]
	v_mfma_f32_16x16x32_bf16 v[68:71], v[162:165], v[180:183], v[68:71]
	v_mfma_f32_16x16x32_bf16 v[68:71], v[166:169], v[184:187], v[68:71]
	v_mfma_f32_16x16x32_bf16 v[56:59], v[172:175], v[180:183], v[56:59]
	v_mfma_f32_16x16x32_bf16 v[56:59], v[176:179], v[184:187], v[56:59]
	v_mfma_f32_16x16x32_bf16 v[48:51], v[162:165], v[196:199], v[48:51]
	v_mfma_f32_16x16x32_bf16 v[48:51], v[166:169], v[200:203], v[48:51]
	v_mfma_f32_16x16x32_bf16 v[40:43], v[172:175], v[196:199], v[40:43]
	v_mfma_f32_16x16x32_bf16 v[40:43], v[176:179], v[200:203], v[40:43]
	v_mfma_f32_16x16x32_bf16 v[32:35], v[162:165], v[204:207], v[32:35]
	v_mfma_f32_16x16x32_bf16 v[32:35], v[166:169], v[208:211], v[32:35]
	v_mfma_f32_16x16x32_bf16 v[24:27], v[172:175], v[204:207], v[24:27]
	v_mfma_f32_16x16x32_bf16 v[24:27], v[176:179], v[208:211], v[24:27]
	v_mfma_f32_16x16x32_bf16 v[16:19], v[162:165], v[212:215], v[16:19]
	v_mfma_f32_16x16x32_bf16 v[16:19], v[166:169], v[216:219], v[16:19]
	v_mfma_f32_16x16x32_bf16 v[8:11], v[172:175], v[212:215], v[8:11]
	v_mfma_f32_16x16x32_bf16 v[8:11], v[176:179], v[216:219], v[8:11]
	s_barrier
	s_setprio 0
	ds_read_b128 v[138:141], v136
	ds_read_b128 v[142:145], v136 offset:1024
	ds_read_b128 v[154:157], v136 offset:2048
	ds_read_b128 v[158:161], v136 offset:3072
	ds_read_b128 v[162:165], v137
	ds_read_b128 v[166:169], v137 offset:1024
	ds_read_b128 v[172:175], v137 offset:2048
	ds_read_b128 v[176:179], v137 offset:3072
	ds_read_b128 v[180:183], v152 offset:32768
	ds_read_b128 v[184:187], v152 offset:33792
	ds_read_b128 v[196:199], v152 offset:34816
	ds_read_b128 v[200:203], v152 offset:35840
	ds_read_b128 v[204:207], v152 offset:36864
	ds_read_b128 v[208:211], v152 offset:37888
	ds_read_b128 v[212:215], v152 offset:38912
	ds_read_b128 v[216:219], v152 offset:39936
	s_add_u32 s88, s88, 0x40000
	s_addc_u32 s89, s89, 0
	s_add_i32 m0, s69, 0x4000
	s_nop 0
	global_load_lds_dwordx4 v147, s[88:89]
	s_nop 0
	s_add_i32 m0, s69, 0x6000
	s_nop 0
	global_load_lds_dwordx4 v148, s[88:89]
	s_waitcnt vmcnt(8)
	s_waitcnt lgkmcnt(0)
	s_setprio 1
	s_barrier
	v_mfma_f32_16x16x32_bf16 v[124:127], v[138:141], v[180:183], v[124:127]
	v_mfma_f32_16x16x32_bf16 v[124:127], v[142:145], v[184:187], v[124:127]
	v_mfma_f32_16x16x32_bf16 v[116:119], v[154:157], v[180:183], v[116:119]
	v_mfma_f32_16x16x32_bf16 v[116:119], v[158:161], v[184:187], v[116:119]
	v_mfma_f32_16x16x32_bf16 v[108:111], v[138:141], v[196:199], v[108:111]
	v_mfma_f32_16x16x32_bf16 v[108:111], v[142:145], v[200:203], v[108:111]
	v_mfma_f32_16x16x32_bf16 v[100:103], v[154:157], v[196:199], v[100:103]
	v_mfma_f32_16x16x32_bf16 v[100:103], v[158:161], v[200:203], v[100:103]
	v_mfma_f32_16x16x32_bf16 v[92:95], v[138:141], v[204:207], v[92:95]
	v_mfma_f32_16x16x32_bf16 v[92:95], v[142:145], v[208:211], v[92:95]
	v_mfma_f32_16x16x32_bf16 v[84:87], v[154:157], v[204:207], v[84:87]
	v_mfma_f32_16x16x32_bf16 v[84:87], v[158:161], v[208:211], v[84:87]
	v_mfma_f32_16x16x32_bf16 v[76:79], v[138:141], v[212:215], v[76:79]
	v_mfma_f32_16x16x32_bf16 v[76:79], v[142:145], v[216:219], v[76:79]
	v_mfma_f32_16x16x32_bf16 v[64:67], v[154:157], v[212:215], v[64:67]
	v_mfma_f32_16x16x32_bf16 v[64:67], v[158:161], v[216:219], v[64:67]
	v_mfma_f32_16x16x32_bf16 v[128:131], v[162:165], v[180:183], v[128:131]
	v_mfma_f32_16x16x32_bf16 v[128:131], v[166:169], v[184:187], v[128:131]
	v_mfma_f32_16x16x32_bf16 v[120:123], v[172:175], v[180:183], v[120:123]
	v_mfma_f32_16x16x32_bf16 v[120:123], v[176:179], v[184:187], v[120:123]
	v_mfma_f32_16x16x32_bf16 v[112:115], v[162:165], v[196:199], v[112:115]
	v_mfma_f32_16x16x32_bf16 v[112:115], v[166:169], v[200:203], v[112:115]
	v_mfma_f32_16x16x32_bf16 v[104:107], v[172:175], v[196:199], v[104:107]
	v_mfma_f32_16x16x32_bf16 v[104:107], v[176:179], v[200:203], v[104:107]
	v_mfma_f32_16x16x32_bf16 v[96:99], v[162:165], v[204:207], v[96:99]
	v_mfma_f32_16x16x32_bf16 v[96:99], v[166:169], v[208:211], v[96:99]
	v_mfma_f32_16x16x32_bf16 v[88:91], v[172:175], v[204:207], v[88:91]
	v_mfma_f32_16x16x32_bf16 v[88:91], v[176:179], v[208:211], v[88:91]
	v_mfma_f32_16x16x32_bf16 v[80:83], v[162:165], v[212:215], v[80:83]
	v_mfma_f32_16x16x32_bf16 v[80:83], v[166:169], v[216:219], v[80:83]
	v_mfma_f32_16x16x32_bf16 v[72:75], v[172:175], v[212:215], v[72:75]
	v_mfma_f32_16x16x32_bf16 v[72:75], v[176:179], v[216:219], v[72:75]
	s_barrier
	s_setprio 0
	ds_read_b128 v[180:183], v152 offset:49152
	ds_read_b128 v[184:187], v152 offset:50176
	ds_read_b128 v[196:199], v152 offset:51200
	ds_read_b128 v[200:203], v152 offset:52224
	ds_read_b128 v[204:207], v152 offset:53248
	ds_read_b128 v[208:211], v152 offset:54272
	ds_read_b128 v[212:215], v152 offset:55296
	ds_read_b128 v[216:219], v152 offset:56320
	s_add_i32 m0, s69, 0x18000
	s_nop 0
	global_load_lds_dwordx4 v1, s[86:87]
	s_nop 0
	s_add_i32 m0, s69, 0x1a000
	s_nop 0
	global_load_lds_dwordx4 v146, s[86:87]
	s_add_u32 s2, s2, 0x40080
	s_addc_u32 s3, s3, 0
	s_add_i32 m0, s69, 0x1c000
	s_nop 0
	global_load_lds_dwordx4 v1, s[2:3]
	s_nop 0
	s_add_i32 m0, s69, 0x1e000
	s_nop 0
	global_load_lds_dwordx4 v146, s[2:3]
	s_nop 0
	s_add_i32 m0, s69, 0x8000
	s_nop 0
	global_load_lds_dwordx4 v147, s[12:13]
	s_nop 0
	s_add_i32 m0, s69, 0xa000
	s_nop 0
	global_load_lds_dwordx4 v148, s[12:13]
	s_waitcnt vmcnt(8)
	s_waitcnt lgkmcnt(0)
	s_setprio 1
	s_barrier
	v_mfma_f32_16x16x32_bf16 v[60:63], v[138:141], v[180:183], v[60:63]
	v_mfma_f32_16x16x32_bf16 v[60:63], v[142:145], v[184:187], v[60:63]
	v_mfma_f32_16x16x32_bf16 v[52:55], v[154:157], v[180:183], v[52:55]
	v_mfma_f32_16x16x32_bf16 v[52:55], v[158:161], v[184:187], v[52:55]
	v_mfma_f32_16x16x32_bf16 v[44:47], v[138:141], v[196:199], v[44:47]
	v_mfma_f32_16x16x32_bf16 v[44:47], v[142:145], v[200:203], v[44:47]
	v_mfma_f32_16x16x32_bf16 v[36:39], v[154:157], v[196:199], v[36:39]
	v_mfma_f32_16x16x32_bf16 v[36:39], v[158:161], v[200:203], v[36:39]
	v_mfma_f32_16x16x32_bf16 v[28:31], v[138:141], v[204:207], v[28:31]
	v_mfma_f32_16x16x32_bf16 v[28:31], v[142:145], v[208:211], v[28:31]
	v_mfma_f32_16x16x32_bf16 v[20:23], v[154:157], v[204:207], v[20:23]
	v_mfma_f32_16x16x32_bf16 v[20:23], v[158:161], v[208:211], v[20:23]
	v_mfma_f32_16x16x32_bf16 v[12:15], v[138:141], v[212:215], v[12:15]
	v_mfma_f32_16x16x32_bf16 v[12:15], v[142:145], v[216:219], v[12:15]
	v_mfma_f32_16x16x32_bf16 v[4:7], v[154:157], v[212:215], v[4:7]
	v_mfma_f32_16x16x32_bf16 v[4:7], v[158:161], v[216:219], v[4:7]
	v_mfma_f32_16x16x32_bf16 v[68:71], v[162:165], v[180:183], v[68:71]
	v_mfma_f32_16x16x32_bf16 v[68:71], v[166:169], v[184:187], v[68:71]
	v_mfma_f32_16x16x32_bf16 v[56:59], v[172:175], v[180:183], v[56:59]
	v_mfma_f32_16x16x32_bf16 v[56:59], v[176:179], v[184:187], v[56:59]
	v_mfma_f32_16x16x32_bf16 v[48:51], v[162:165], v[196:199], v[48:51]
	v_mfma_f32_16x16x32_bf16 v[48:51], v[166:169], v[200:203], v[48:51]
	v_mfma_f32_16x16x32_bf16 v[40:43], v[172:175], v[196:199], v[40:43]
	v_mfma_f32_16x16x32_bf16 v[40:43], v[176:179], v[200:203], v[40:43]
	v_mfma_f32_16x16x32_bf16 v[32:35], v[162:165], v[204:207], v[32:35]
	v_mfma_f32_16x16x32_bf16 v[32:35], v[166:169], v[208:211], v[32:35]
	v_mfma_f32_16x16x32_bf16 v[24:27], v[172:175], v[204:207], v[24:27]
	v_mfma_f32_16x16x32_bf16 v[24:27], v[176:179], v[208:211], v[24:27]
	v_mfma_f32_16x16x32_bf16 v[16:19], v[162:165], v[212:215], v[16:19]
	v_mfma_f32_16x16x32_bf16 v[16:19], v[166:169], v[216:219], v[16:19]
	v_mfma_f32_16x16x32_bf16 v[8:11], v[172:175], v[212:215], v[8:11]
	v_mfma_f32_16x16x32_bf16 v[8:11], v[176:179], v[216:219], v[8:11]
	s_barrier
	s_setprio 0
	s_add_i32 s2, s29, 2
	s_cmp_gt_u32 s29, 13
	s_cbranch_scc1 .LBB0_1196
	s_mov_b32 s29, s2
	s_branch .LBB0_1072
